# t9 + G_in/G_up epilogue rstd row loads issued at unit start (before the K-loop) into spare VGPRs, epilogue copies them instead of loading
# speedup vs baseline: 1.0021x; 1.0005x over previous
; template <class Epi, class Sched, bool ALIGN_EPI = false, bool SP2 = false, bool SLIVER = false>
; __device__ __forceinline__ void gemm_phase(PG8_LAS unsigned char* lds, const Gemm g, const Sched& S, const Epi& E) {
;     ...
;         const bool has_next = S.next(ui + 1, nxt);
;         const char* nA = has_next ? (const char*)g.A + (size_t)nxt.pm * tstep + Epi::k0(nxt.seg) * 2 : cA; const char* nB = has_next ? (const char*)g.Bt + (size_t)nxt.pn * tstep + Epi::k0(nxt.seg) * 2 : cB;
;         const char* nS = has_next ? (const char*)g.A + (size_t)S.srow0 * K * 2 + (size_t)nxt.pm * sstep + Epi::k0(nxt.seg) * 2 : cS;
;     ...
;         if (fin) {
; #pragma unroll
;         for (int a = 0; a < 2; ++a)
; #pragma unroll
;             for (int b = 0; b < 2; ++b)
; #pragma unroll
;                 for (int m = 0; m < 4; ++m)
; #pragma unroll
;                     for (int n = 0; n < 2; ++n) acc[a][b][m][n] = (f32x4){0.f, 0.f, 0.f, 0.f};
;         accs[0] = (f32x4){0.f, 0.f, 0.f, 0.f}; accs[1] = (f32x4){0.f, 0.f, 0.f, 0.f};
;         }
;         cur = nxt; cA = nA; cB = nB; cS = nS; nt = Epi::nt(cur.seg, K); ++ui;
.LBB0_152:
	v_and_b32_e32 v208, 15, v0
	s_lshl_b32 s36, s92, 8
	s_add_i32 s36, s36, s16
	v_or_b32_e32 v208, s36, v208
	v_ashrrev_i32_e32 v209, 31, v208
	v_lshl_add_u64 v[234:235], v[208:209], 4, s[18:19]
	global_load_dwordx4 v[214:217], v[234:235], off
	global_load_dwordx4 v[218:221], v[234:235], off offset:256
	global_load_dwordx4 v[222:225], v[234:235], off offset:512
	global_load_dwordx4 v[226:229], v[234:235], off offset:768
	global_load_dwordx4 v[230:233], v[234:235], off offset:2048
	global_load_dwordx4 v[240:243], v[234:235], off offset:2304
	global_load_dwordx4 v[244:247], v[234:235], off offset:2560
	global_load_dwordx4 v[248:251], v[234:235], off offset:2816
	s_ashr_i32 s85, s84, 31
	s_lshl_b64 s[12:13], s[84:85], 20
	s_add_u32 s86, s96, s12
	s_addc_u32 s87, s97, s13
	s_and_b64 s[12:13], s[38:39], exec
	s_cselect_b32 s12, s87, s81
	s_cselect_b32 s13, s86, s80
	s_ashr_i32 s83, s82, 31
	s_lshl_b64 s[40:41], s[82:83], 20
	v_readlane_b32 s66, v254, 43
	s_add_u32 s88, s66, s40
	s_addc_u32 s89, s52, s41
	s_and_b64 s[40:41], s[38:39], exec
	s_cselect_b32 s66, s89, s63
	s_cselect_b32 s67, s88, s62
	s_add_u32 s40, s80, 0x80080
	s_addc_u32 s41, s81, 0
	s_add_u32 s68, s62, 0x100
	v_mov_b32_e32 v2, 0
	s_addc_u32 s69, s63, 0
	s_mov_b32 s76, -2
	v_mov_b32_e32 v3, v2
	v_mov_b32_e32 v4, v2
	v_mov_b32_e32 v5, v2
	v_mov_b32_e32 v6, v2
	v_mov_b32_e32 v7, v2
	v_mov_b32_e32 v8, v2
	v_mov_b32_e32 v9, v2
	v_mov_b32_e32 v14, v2
	v_mov_b32_e32 v15, v2
	v_mov_b32_e32 v16, v2
	v_mov_b32_e32 v17, v2
	v_mov_b32_e32 v22, v2
	v_mov_b32_e32 v23, v2
	v_mov_b32_e32 v24, v2
	v_mov_b32_e32 v25, v2
	v_mov_b32_e32 v30, v2
	v_mov_b32_e32 v31, v2
	v_mov_b32_e32 v32, v2
	v_mov_b32_e32 v33, v2
	v_mov_b32_e32 v38, v2
	v_mov_b32_e32 v39, v2
	v_mov_b32_e32 v40, v2
	v_mov_b32_e32 v41, v2
	v_mov_b32_e32 v46, v2
	v_mov_b32_e32 v47, v2
	v_mov_b32_e32 v48, v2
	v_mov_b32_e32 v49, v2
	v_mov_b32_e32 v54, v2
	v_mov_b32_e32 v55, v2
	v_mov_b32_e32 v56, v2
	v_mov_b32_e32 v57, v2
	v_mov_b32_e32 v10, v2
	v_mov_b32_e32 v11, v2
	v_mov_b32_e32 v12, v2
	v_mov_b32_e32 v13, v2
	v_mov_b32_e32 v18, v2
	v_mov_b32_e32 v19, v2
	v_mov_b32_e32 v20, v2
	v_mov_b32_e32 v21, v2
	v_mov_b32_e32 v26, v2
	v_mov_b32_e32 v27, v2
	v_mov_b32_e32 v28, v2
	v_mov_b32_e32 v29, v2
	v_mov_b32_e32 v34, v2
	v_mov_b32_e32 v35, v2
	v_mov_b32_e32 v36, v2
	v_mov_b32_e32 v37, v2
	v_mov_b32_e32 v42, v2
	v_mov_b32_e32 v43, v2
	v_mov_b32_e32 v44, v2
	v_mov_b32_e32 v45, v2
	v_mov_b32_e32 v50, v2
	v_mov_b32_e32 v51, v2
	v_mov_b32_e32 v52, v2
	v_mov_b32_e32 v53, v2
	v_mov_b32_e32 v58, v2
	v_mov_b32_e32 v59, v2
	v_mov_b32_e32 v60, v2
	v_mov_b32_e32 v61, v2
	v_mov_b32_e32 v62, v2
	v_mov_b32_e32 v63, v2
	v_mov_b32_e32 v64, v2
	v_mov_b32_e32 v65, v2
	v_mov_b32_e32 v66, v2
	v_mov_b32_e32 v67, v2
	v_mov_b32_e32 v68, v2
	v_mov_b32_e32 v69, v2
	v_mov_b32_e32 v70, v2
	v_mov_b32_e32 v71, v2
	v_mov_b32_e32 v72, v2
	v_mov_b32_e32 v73, v2
	v_mov_b32_e32 v78, v2
	v_mov_b32_e32 v79, v2
	v_mov_b32_e32 v80, v2
	v_mov_b32_e32 v81, v2
	v_mov_b32_e32 v86, v2
	v_mov_b32_e32 v87, v2
	v_mov_b32_e32 v88, v2
	v_mov_b32_e32 v89, v2
	v_mov_b32_e32 v94, v2
	v_mov_b32_e32 v95, v2
	v_mov_b32_e32 v96, v2
	v_mov_b32_e32 v97, v2
	v_mov_b32_e32 v102, v2
	v_mov_b32_e32 v103, v2
	v_mov_b32_e32 v104, v2
	v_mov_b32_e32 v105, v2
	v_mov_b32_e32 v110, v2
	v_mov_b32_e32 v111, v2
	v_mov_b32_e32 v112, v2
	v_mov_b32_e32 v113, v2
	v_mov_b32_e32 v118, v2
	v_mov_b32_e32 v119, v2
	v_mov_b32_e32 v120, v2
	v_mov_b32_e32 v121, v2
	v_mov_b32_e32 v74, v2
	v_mov_b32_e32 v75, v2
	v_mov_b32_e32 v76, v2
	v_mov_b32_e32 v77, v2
	v_mov_b32_e32 v82, v2
	v_mov_b32_e32 v83, v2
	v_mov_b32_e32 v84, v2
	v_mov_b32_e32 v85, v2
	v_mov_b32_e32 v90, v2
	v_mov_b32_e32 v91, v2
	v_mov_b32_e32 v92, v2
	v_mov_b32_e32 v93, v2
	v_mov_b32_e32 v98, v2
	v_mov_b32_e32 v99, v2
	v_mov_b32_e32 v100, v2
	v_mov_b32_e32 v101, v2
	v_mov_b32_e32 v106, v2
	v_mov_b32_e32 v107, v2
	v_mov_b32_e32 v108, v2
	v_mov_b32_e32 v109, v2
	v_mov_b32_e32 v114, v2
	v_mov_b32_e32 v115, v2
	v_mov_b32_e32 v116, v2
	v_mov_b32_e32 v117, v2
	v_mov_b32_e32 v122, v2
	v_mov_b32_e32 v123, v2
	v_mov_b32_e32 v124, v2
	v_mov_b32_e32 v125, v2
	v_mov_b32_e32 v126, v2
	v_mov_b32_e32 v127, v2
	v_mov_b32_e32 v128, v2
	v_mov_b32_e32 v129, v2

; __device__ __forceinline__ float ss_total(const u32x4 a) { return ((bflo(a.x) + bfhi(a.x)) + (bflo(a.y) + bfhi(a.y))) + ((bflo(a.z) + bfhi(a.z)) + (bflo(a.w) + bfhi(a.w))); }
; __device__ __forceinline__ float row_rstd(const bf16_t* ss, int row) { const u32x4 a = *(const u32x4*)(ss + (size_t)row * 8);
;     return __builtin_amdgcn_rsqf(ss_total(a) * (1.f / 2048.f) + 1e-6f); }
;     __device__ __forceinline__ void operator()(const f32x4 (&acc)[2][2][4][2], const Unit& u, int wr, int wc, int fr, int fq) const {
;         const int pn = u.pn, rowt = u.pm * BM + wr * 64 + fr, colw = wc * 32 + 8 * fq;
;         float rsv[2][4];
; #pragma unroll
;         for (int ai = 0; ai < 2; ++ai)
; #pragma unroll
;             for (int m = 0; m < 4; ++m) rsv[ai][m] = row_rstd(ss, rowt + ai * HALF + m * 16);
;         if (pn < 20 || pn >= 36) {
.LBB0_156:
	v_mov_b32_e32 v138, v0
	s_lshl_b32 s12, s92, 8
	s_add_i32 s12, s12, s16
	v_and_b32_e32 v159, 15, v138
	v_or_b32_e32 v156, s12, v159
	v_ashrrev_i32_e32 v157, 31, v156
	v_or_b32_e32 v154, 16, v156
	v_lshl_add_u64 v[136:137], v[156:157], 4, s[18:19]
	v_ashrrev_i32_e32 v155, 31, v154
	v_or_b32_e32 v150, 32, v156
	v_mov_b32_e32 v160, v214
	v_mov_b32_e32 v161, v215
	v_mov_b32_e32 v162, v216
	v_mov_b32_e32 v163, v217
	v_lshl_add_u64 v[136:137], v[154:155], 4, s[18:19]
	v_ashrrev_i32_e32 v151, 31, v150
	v_mov_b32_e32 v164, v218
	v_mov_b32_e32 v165, v219
	v_mov_b32_e32 v166, v220
	v_mov_b32_e32 v167, v221
	v_lshl_add_u64 v[136:137], v[150:151], 4, s[18:19]
	v_mov_b32_e32 v168, v222
	v_mov_b32_e32 v169, v223
	v_mov_b32_e32 v170, v224
	v_mov_b32_e32 v171, v225
	v_or_b32_e32 v146, 48, v156
	v_ashrrev_i32_e32 v147, 31, v146
	v_lshl_add_u64 v[136:137], v[146:147], 4, s[18:19]
	v_mov_b32_e32 v172, v226
	v_mov_b32_e32 v173, v227
	v_mov_b32_e32 v174, v228
	v_mov_b32_e32 v175, v229
	v_add_u32_e32 v142, 0x80, v156
	v_ashrrev_i32_e32 v143, 31, v142
	v_lshl_add_u64 v[136:137], v[142:143], 4, s[18:19]
	v_mov_b32_e32 v180, v230
	v_mov_b32_e32 v181, v231
	v_mov_b32_e32 v182, v232
	v_mov_b32_e32 v183, v233
	v_add_u32_e32 v140, 0x90, v156
	v_add_u32_e32 v136, 0xb0, v156
	v_lshrrev_b32_e32 v178, 1, v138
	v_add_u32_e32 v138, 0xa0, v156
	v_ashrrev_i32_e32 v141, 31, v140
	v_ashrrev_i32_e32 v137, 31, v136
	v_ashrrev_i32_e32 v139, 31, v138
	v_lshl_add_u64 v[152:153], v[140:141], 4, s[18:19]
	v_lshl_add_u64 v[192:193], v[136:137], 4, s[18:19]
	v_lshl_add_u64 v[176:177], v[138:139], 4, s[18:19]
	v_mov_b32_e32 v184, v240
	v_mov_b32_e32 v185, v241
	v_mov_b32_e32 v186, v242
	v_mov_b32_e32 v187, v243
	v_mov_b32_e32 v188, v244
	v_mov_b32_e32 v189, v245
	v_mov_b32_e32 v190, v246
	v_mov_b32_e32 v191, v247
	s_nop 0
	v_mov_b32_e32 v192, v248
	v_mov_b32_e32 v193, v249
	v_mov_b32_e32 v194, v250
	v_mov_b32_e32 v195, v251
	s_sub_i32 s12, s90, 36
	s_cmp_gt_u32 s12, 0xffffffef
	s_mov_b64 s[12:13], -1
	v_readlane_b32 s79, v254, 35
	s_movk_i32 s77, 0x70
	s_mov_b64 s[68:69], 0x4000c00
	s_waitcnt vmcnt(0)
	v_lshlrev_b32_e32 v144, 16, v160
	v_and_b32_e32 v148, 0xffff0000, v160
	v_lshlrev_b32_e32 v152, 16, v161
	v_and_b32_e32 v153, 0xffff0000, v161
	v_lshlrev_b32_e32 v158, 16, v162
	v_and_b32_e32 v160, 0xffff0000, v162
	v_lshlrev_b32_e32 v161, 16, v163
	v_and_b32_e32 v162, 0xffff0000, v163
	v_add_f32_e32 v144, v144, v148
	v_add_f32_e32 v148, v152, v153
	v_add_f32_e32 v152, v158, v160
	v_add_f32_e32 v153, v161, v162
	v_lshlrev_b32_e32 v158, 16, v164
	v_and_b32_e32 v160, 0xffff0000, v164
	v_lshlrev_b32_e32 v161, 16, v165
	v_and_b32_e32 v162, 0xffff0000, v165
	v_lshlrev_b32_e32 v163, 16, v166
	v_and_b32_e32 v164, 0xffff0000, v166
	v_lshlrev_b32_e32 v165, 16, v167
	v_and_b32_e32 v166, 0xffff0000, v167
	v_lshlrev_b32_e32 v167, 16, v168
	v_and_b32_e32 v168, 0xffff0000, v168
	v_lshlrev_b32_e32 v176, 16, v169
	v_and_b32_e32 v169, 0xffff0000, v169
	v_lshlrev_b32_e32 v177, 16, v170
	v_and_b32_e32 v170, 0xffff0000, v170
	v_lshlrev_b32_e32 v196, 16, v171
	v_and_b32_e32 v171, 0xffff0000, v171
	v_add_f32_e32 v144, v144, v148
	v_add_f32_e32 v148, v152, v153
	v_add_f32_e32 v152, v158, v160
	v_add_f32_e32 v153, v161, v162
	v_add_f32_e32 v158, v163, v164
	v_add_f32_e32 v160, v165, v166
	v_add_f32_e32 v161, v167, v168
	v_add_f32_e32 v162, v176, v169
	v_add_f32_e32 v163, v177, v170
	v_add_f32_e32 v164, v196, v171
	v_add_f32_e32 v144, v144, v148
	v_add_f32_e32 v148, v152, v153
	v_add_f32_e32 v152, v158, v160
	v_add_f32_e32 v153, v161, v162
	v_add_f32_e32 v158, v163, v164
	v_fmamk_f32 v144, v144, 0x3a000000, v1
	v_add_f32_e32 v148, v148, v152
	v_add_f32_e32 v152, v153, v158
	v_rsq_f32_e32 v166, v144
	v_fmamk_f32 v144, v148, 0x3a000000, v1
	v_fmamk_f32 v148, v152, 0x3a000000, v1
	v_rsq_f32_e32 v162, v148
	v_lshlrev_b32_e32 v148, 16, v174
	v_and_b32_e32 v152, 0xffff0000, v174
	v_lshlrev_b32_e32 v197, 16, v172
	v_and_b32_e32 v172, 0xffff0000, v172
	v_lshlrev_b32_e32 v198, 16, v173
	v_rsq_f32_e32 v164, v144
	v_and_b32_e32 v144, 0xffff0000, v173
	v_add_f32_e32 v148, v148, v152
	v_lshlrev_b32_e32 v152, 16, v175
	v_and_b32_e32 v153, 0xffff0000, v175
	v_add_f32_e32 v165, v197, v172
	v_add_f32_e32 v144, v198, v144
	v_add_f32_e32 v152, v152, v153
	v_add_f32_e32 v144, v165, v144
	v_add_f32_e32 v148, v148, v152
	v_add_f32_e32 v144, v144, v148
	v_fmamk_f32 v144, v144, 0x3a000000, v1
	v_rsq_f32_e32 v160, v144
	v_lshlrev_b32_e32 v144, 16, v180
	v_and_b32_e32 v148, 0xffff0000, v180
	v_add_f32_e32 v144, v144, v148
	v_lshlrev_b32_e32 v148, 16, v181
	v_and_b32_e32 v152, 0xffff0000, v181
	v_add_f32_e32 v148, v148, v152
	v_add_f32_e32 v144, v144, v148
	v_lshlrev_b32_e32 v148, 16, v182
	v_and_b32_e32 v152, 0xffff0000, v182
	v_add_f32_e32 v148, v148, v152
	v_lshlrev_b32_e32 v152, 16, v183
	v_and_b32_e32 v153, 0xffff0000, v183
	v_add_f32_e32 v152, v152, v153
	v_add_f32_e32 v148, v148, v152
	v_add_f32_e32 v144, v144, v148
	v_fmamk_f32 v144, v144, 0x3a000000, v1
	v_rsq_f32_e32 v158, v144
	v_lshlrev_b32_e32 v144, 16, v184
	v_and_b32_e32 v148, 0xffff0000, v184
	v_add_f32_e32 v144, v144, v148
	v_lshlrev_b32_e32 v148, 16, v185
	v_and_b32_e32 v152, 0xffff0000, v185
	v_add_f32_e32 v148, v148, v152
	v_add_f32_e32 v144, v144, v148
	v_lshlrev_b32_e32 v148, 16, v186
	v_and_b32_e32 v152, 0xffff0000, v186
	v_add_f32_e32 v148, v148, v152
	v_lshlrev_b32_e32 v152, 16, v187
	v_and_b32_e32 v153, 0xffff0000, v187
	v_add_f32_e32 v152, v152, v153
	v_add_f32_e32 v148, v148, v152
	v_add_f32_e32 v144, v144, v148
	v_fmamk_f32 v144, v144, 0x3a000000, v1
	v_rsq_f32_e32 v152, v144
	v_lshlrev_b32_e32 v144, 16, v188
	v_and_b32_e32 v148, 0xffff0000, v188
	v_add_f32_e32 v144, v144, v148
	v_lshlrev_b32_e32 v148, 16, v189
	v_and_b32_e32 v153, 0xffff0000, v189
	v_add_f32_e32 v148, v148, v153
	v_add_f32_e32 v144, v144, v148
	v_lshlrev_b32_e32 v148, 16, v190
	v_and_b32_e32 v153, 0xffff0000, v190
	v_add_f32_e32 v148, v148, v153
	v_lshlrev_b32_e32 v153, 16, v191
	v_and_b32_e32 v161, 0xffff0000, v191
	v_add_f32_e32 v153, v153, v161
	v_add_f32_e32 v148, v148, v153
	v_add_f32_e32 v144, v144, v148
	v_fmamk_f32 v144, v144, 0x3a000000, v1
	v_rsq_f32_e32 v148, v144
	v_lshlrev_b32_e32 v144, 16, v192
	v_and_b32_e32 v153, 0xffff0000, v192
	v_add_f32_e32 v144, v144, v153
	v_lshlrev_b32_e32 v153, 16, v193
	v_and_b32_e32 v161, 0xffff0000, v193
	v_add_f32_e32 v153, v153, v161
	v_add_f32_e32 v144, v144, v153
	v_lshlrev_b32_e32 v153, 16, v194
	v_and_b32_e32 v161, 0xffff0000, v194
	v_add_f32_e32 v153, v153, v161
	v_lshlrev_b32_e32 v161, 16, v195
	v_and_b32_e32 v163, 0xffff0000, v195
	v_add_f32_e32 v161, v161, v163
	v_add_f32_e32 v153, v153, v161
	v_add_f32_e32 v144, v144, v153
	v_fmamk_f32 v144, v144, 0x3a000000, v1
	v_rsq_f32_e32 v144, v144
	v_and_or_b32 v153, v178, 24, s17
	s_cbranch_scc0 .LBB0_195
;     __device__ __forceinline__ void operator()(const f32x4 (&acc)[2][2][4][2], const Unit& u, int wr, int wc, int fr, int fq) const {
;     ...
;         } else {
;             const bool isv = pn >= 28; const int colt = (pn - (isv ? 28 : 20)) * 256 + colw;
;             float* fbase; bf16_t* bbase;
;             if (u.pm < 32) { fbase = out + (isv ? O_VP : O_KP) + (size_t)L * MP * DM; bbase = (bf16_t*)(ws + (isv ? WS_VB : WS_KB)); }
;             else { fbase = out + (isv ? O_VS : O_KS) + (size_t)L * MS * DM; bbase = (bf16_t*)(ws + (isv ? WS_VALL : WS_KALL)) + (size_t)L * DB * KROWS * DM; }
	s_cmp_gt_u32 s90, 27
	s_cselect_b64 s[40:41], -1, 0
	s_cmp_gt_i32 s92, 31
	s_cselect_b64 s[92:93], -1, 0
	s_mov_b64 s[94:95], -1
	s_and_b64 vcc, exec, s[92:93]
	s_cbranch_vccz .LBB0_159
	s_and_b64 s[12:13], s[40:41], exec
	s_mov_b32 s12, 0x25420000
	s_cselect_b32 s12, s12, 0x24420000
	v_readlane_b32 s13, v254, 50
	s_add_u32 s62, s13, s12
	v_readlane_b32 s12, v254, 53
	s_addc_u32 s63, s12, 0
	s_and_b64 s[12:13], s[40:41], exec
	s_mov_b32 s12, 0x2dd00000
	s_cselect_b32 s12, s12, 0x24d00000
	v_readlane_b32 s13, v254, 47
	s_add_u32 s80, s13, s12
	v_readlane_b32 s12, v254, 48
	s_addc_u32 s81, s12, 0
	s_mov_b64 s[94:95], 0

; template <class Epi, class Sched, bool ALIGN_EPI = false, bool SP2 = false, bool SLIVER = false>
; __device__ __forceinline__ void gemm_phase(PG8_LAS unsigned char* lds, const Gemm g, const Sched& S, const Epi& E) {
;     ...
;         const bool has_next = S.next(ui + 1, nxt);
;         const char* nA = has_next ? (const char*)g.A + (size_t)nxt.pm * tstep + Epi::k0(nxt.seg) * 2 : cA; const char* nB = has_next ? (const char*)g.Bt + (size_t)nxt.pn * tstep + Epi::k0(nxt.seg) * 2 : cB;
;         const char* nS = has_next ? (const char*)g.A + (size_t)S.srow0 * K * 2 + (size_t)nxt.pm * sstep + Epi::k0(nxt.seg) * 2 : cS;
;     ...
;         if (fin) {
; #pragma unroll
;         for (int a = 0; a < 2; ++a)
; #pragma unroll
;             for (int b = 0; b < 2; ++b)
; #pragma unroll
;                 for (int m = 0; m < 4; ++m)
; #pragma unroll
;                     for (int n = 0; n < 2; ++n) acc[a][b][m][n] = (f32x4){0.f, 0.f, 0.f, 0.f};
;         accs[0] = (f32x4){0.f, 0.f, 0.f, 0.f}; accs[1] = (f32x4){0.f, 0.f, 0.f, 0.f};
;         }
;         cur = nxt; cA = nA; cB = nB; cS = nS; nt = Epi::nt(cur.seg, K); ++ui;
.LBB0_704:
	v_and_b32_e32 v208, 15, v0
	s_lshl_b32 s36, s82, 8
	s_add_i32 s36, s36, s10
	v_or_b32_e32 v208, s36, v208
	v_ashrrev_i32_e32 v209, 31, v208
	v_lshl_add_u64 v[234:235], v[208:209], 4, s[40:41]
	global_load_dwordx4 v[214:217], v[234:235], off
	global_load_dwordx4 v[218:221], v[234:235], off offset:256
	global_load_dwordx4 v[222:225], v[234:235], off offset:512
	global_load_dwordx4 v[226:229], v[234:235], off offset:768
	global_load_dwordx4 v[230:233], v[234:235], off offset:2048
	global_load_dwordx4 v[240:243], v[234:235], off offset:2304
	global_load_dwordx4 v[244:247], v[234:235], off offset:2560
	global_load_dwordx4 v[248:251], v[234:235], off offset:2816
	s_ashr_i32 s51, s50, 31
	s_lshl_b64 s[52:53], s[50:51], 20
	s_add_u32 s52, s84, s52
	s_addc_u32 s53, s85, s53
	s_and_b64 s[54:55], s[38:39], exec
	s_cselect_b32 s3, s53, s63
	s_cselect_b32 s51, s52, s62
	s_ashr_i32 s49, s48, 31
	s_lshl_b64 s[54:55], s[48:49], 20
	s_add_u32 s54, s86, s54
	s_addc_u32 s55, s87, s55
	s_and_b64 s[66:67], s[38:39], exec
	s_cselect_b32 s49, s55, s81
	s_cselect_b32 s66, s54, s80
	s_add_u32 s62, s62, 0x80080
	s_addc_u32 s63, s63, 0
	s_add_u32 s67, s80, 0x100
	v_mov_b32_e32 v2, 0
	s_addc_u32 s68, s81, 0
	s_mov_b32 s69, -2
	v_mov_b32_e32 v3, v2
	v_mov_b32_e32 v4, v2
	v_mov_b32_e32 v5, v2
	v_mov_b32_e32 v10, v2
	v_mov_b32_e32 v11, v2
	v_mov_b32_e32 v12, v2
	v_mov_b32_e32 v13, v2
	v_mov_b32_e32 v18, v2
	v_mov_b32_e32 v19, v2
	v_mov_b32_e32 v20, v2
	v_mov_b32_e32 v21, v2
	v_mov_b32_e32 v26, v2
	v_mov_b32_e32 v27, v2
	v_mov_b32_e32 v28, v2
	v_mov_b32_e32 v29, v2
	v_mov_b32_e32 v34, v2
	v_mov_b32_e32 v35, v2
	v_mov_b32_e32 v36, v2
	v_mov_b32_e32 v37, v2
	v_mov_b32_e32 v42, v2
	v_mov_b32_e32 v43, v2
	v_mov_b32_e32 v44, v2
	v_mov_b32_e32 v45, v2
	v_mov_b32_e32 v50, v2
	v_mov_b32_e32 v51, v2
	v_mov_b32_e32 v52, v2
	v_mov_b32_e32 v53, v2
	v_mov_b32_e32 v58, v2
	v_mov_b32_e32 v59, v2
	v_mov_b32_e32 v60, v2
	v_mov_b32_e32 v61, v2
	v_mov_b32_e32 v6, v2
	v_mov_b32_e32 v7, v2
	v_mov_b32_e32 v8, v2
	v_mov_b32_e32 v9, v2
	v_mov_b32_e32 v14, v2
	v_mov_b32_e32 v15, v2
	v_mov_b32_e32 v16, v2
	v_mov_b32_e32 v17, v2
	v_mov_b32_e32 v22, v2
	v_mov_b32_e32 v23, v2
	v_mov_b32_e32 v24, v2
	v_mov_b32_e32 v25, v2
	v_mov_b32_e32 v30, v2
	v_mov_b32_e32 v31, v2
	v_mov_b32_e32 v32, v2
	v_mov_b32_e32 v33, v2
	v_mov_b32_e32 v38, v2
	v_mov_b32_e32 v39, v2
	v_mov_b32_e32 v40, v2
	v_mov_b32_e32 v41, v2
	v_mov_b32_e32 v46, v2
	v_mov_b32_e32 v47, v2
	v_mov_b32_e32 v48, v2
	v_mov_b32_e32 v49, v2
	v_mov_b32_e32 v54, v2
	v_mov_b32_e32 v55, v2
	v_mov_b32_e32 v56, v2
	v_mov_b32_e32 v57, v2
	v_mov_b32_e32 v62, v2
	v_mov_b32_e32 v63, v2
	v_mov_b32_e32 v64, v2
	v_mov_b32_e32 v65, v2
	v_mov_b32_e32 v66, v2
	v_mov_b32_e32 v67, v2
	v_mov_b32_e32 v68, v2
	v_mov_b32_e32 v69, v2
	v_mov_b32_e32 v74, v2
	v_mov_b32_e32 v75, v2
	v_mov_b32_e32 v76, v2
	v_mov_b32_e32 v77, v2
	v_mov_b32_e32 v82, v2
	v_mov_b32_e32 v83, v2
	v_mov_b32_e32 v84, v2
	v_mov_b32_e32 v85, v2
	v_mov_b32_e32 v90, v2
	v_mov_b32_e32 v91, v2
	v_mov_b32_e32 v92, v2
	v_mov_b32_e32 v93, v2
	v_mov_b32_e32 v98, v2
	v_mov_b32_e32 v99, v2
	v_mov_b32_e32 v100, v2
	v_mov_b32_e32 v101, v2
	v_mov_b32_e32 v106, v2
	v_mov_b32_e32 v107, v2
	v_mov_b32_e32 v108, v2
	v_mov_b32_e32 v109, v2
	v_mov_b32_e32 v114, v2
	v_mov_b32_e32 v115, v2
	v_mov_b32_e32 v116, v2
	v_mov_b32_e32 v117, v2
	v_mov_b32_e32 v122, v2
	v_mov_b32_e32 v123, v2
	v_mov_b32_e32 v124, v2
	v_mov_b32_e32 v125, v2
	v_mov_b32_e32 v70, v2
	v_mov_b32_e32 v71, v2
	v_mov_b32_e32 v72, v2
	v_mov_b32_e32 v73, v2
	v_mov_b32_e32 v78, v2
	v_mov_b32_e32 v79, v2
	v_mov_b32_e32 v80, v2
	v_mov_b32_e32 v81, v2
	v_mov_b32_e32 v86, v2
	v_mov_b32_e32 v87, v2
	v_mov_b32_e32 v88, v2
	v_mov_b32_e32 v89, v2
	v_mov_b32_e32 v94, v2
	v_mov_b32_e32 v95, v2
	v_mov_b32_e32 v96, v2
	v_mov_b32_e32 v97, v2
	v_mov_b32_e32 v102, v2
	v_mov_b32_e32 v103, v2
	v_mov_b32_e32 v104, v2
	v_mov_b32_e32 v105, v2
	v_mov_b32_e32 v110, v2
	v_mov_b32_e32 v111, v2
	v_mov_b32_e32 v112, v2
	v_mov_b32_e32 v113, v2
	v_mov_b32_e32 v118, v2
	v_mov_b32_e32 v119, v2
	v_mov_b32_e32 v120, v2
	v_mov_b32_e32 v121, v2
	v_mov_b32_e32 v126, v2
	v_mov_b32_e32 v127, v2
	v_mov_b32_e32 v128, v2
	v_mov_b32_e32 v129, v2

; __device__ __forceinline__ float ss_total(const u32x4 a) { return ((bflo(a.x) + bfhi(a.x)) + (bflo(a.y) + bfhi(a.y))) + ((bflo(a.z) + bfhi(a.z)) + (bflo(a.w) + bfhi(a.w))); }
; __device__ __forceinline__ float row_rstd(const bf16_t* ss, int row) { const u32x4 a = *(const u32x4*)(ss + (size_t)row * 8);
;     return __builtin_amdgcn_rsqf(ss_total(a) * (1.f / 2048.f) + 1e-6f); }
;     __device__ __forceinline__ void operator()(const f32x4 (&acc)[2][2][4][2], const Unit& u, int wr, int wc, int fr, int fq) const {
;         const int rowt = u.pm * BM + wr * 64 + fr, col0 = u.pn * HALF + wc * 32 + 8 * fq;
;         float rsv[2][4];
; #pragma unroll
;         for (int ai = 0; ai < 2; ++ai)
; #pragma unroll
;             for (int m = 0; m < 4; ++m) rsv[ai][m] = row_rstd(ss, rowt + ai * HALF + m * 16);
.LBB0_708:
	s_lshl_b32 s3, s82, 8
	v_mov_b32_e32 v130, v0
	s_add_i32 s3, s3, s10
	s_lshl_b32 s2, s2, 7
	v_and_or_b32 v164, v130, 15, s3
	v_ashrrev_i32_e32 v165, 31, v164
	v_lshrrev_b32_e32 v151, 1, v130
	v_mov_b32_e32 v210, v214
	v_mov_b32_e32 v211, v215
	v_mov_b32_e32 v212, v216
	v_mov_b32_e32 v213, v217
	v_or_b32_e32 v160, 16, v164
	v_ashrrev_i32_e32 v161, 31, v160
	v_or_b32_e32 v156, 32, v164
	v_ashrrev_i32_e32 v157, 31, v156
	v_or_b32_e32 v152, 48, v164
	v_ashrrev_i32_e32 v153, 31, v152
	v_add_u32_e32 v148, 0x80, v164
	v_ashrrev_i32_e32 v149, 31, v148
	v_add_u32_e32 v144, 0x90, v164
	v_ashrrev_i32_e32 v145, 31, v144
	v_mov_b32_e32 v180, v218
	v_mov_b32_e32 v181, v219
	v_mov_b32_e32 v182, v220
	v_mov_b32_e32 v183, v221
	v_mov_b32_e32 v184, v222
	v_mov_b32_e32 v185, v223
	v_mov_b32_e32 v186, v224
	v_mov_b32_e32 v187, v225
	v_mov_b32_e32 v188, v226
	v_mov_b32_e32 v189, v227
	v_mov_b32_e32 v190, v228
	v_mov_b32_e32 v191, v229
	v_mov_b32_e32 v192, v230
	v_mov_b32_e32 v193, v231
	v_mov_b32_e32 v194, v232
	v_mov_b32_e32 v195, v233
	v_mov_b32_e32 v196, v240
	v_mov_b32_e32 v197, v241
	v_mov_b32_e32 v198, v242
	v_mov_b32_e32 v199, v243
	v_mov_b32_e32 v200, v244
	v_mov_b32_e32 v201, v245
	v_mov_b32_e32 v202, v246
	v_mov_b32_e32 v203, v247
	v_mov_b32_e32 v130, v248
	v_mov_b32_e32 v131, v249
	v_mov_b32_e32 v132, v250
	v_mov_b32_e32 v133, v251
	s_movk_i32 s49, 0x2c00
	s_mov_b64 s[62:63], -1
	s_andn2_b64 vcc, exec, s[38:39]
	v_readlane_b32 s79, v254, 35
	s_movk_i32 s77, 0x70
	s_mov_b64 s[68:69], 0x4000c00
	s_waitcnt vmcnt(7)
	v_lshlrev_b32_e32 v139, 16, v212
	v_lshlrev_b32_e32 v138, 16, v210
	v_and_b32_e32 v141, 0xffff0000, v212
	v_and_b32_e32 v140, 0xffff0000, v210
	v_pk_add_f32 v[138:139], v[138:139], v[140:141]
	v_lshlrev_b32_e32 v141, 16, v213
	v_lshlrev_b32_e32 v140, 16, v211
	v_and_b32_e32 v213, 0xffff0000, v213
	v_and_b32_e32 v212, 0xffff0000, v211
	v_pk_add_f32 v[210:211], v[140:141], v[212:213]
	s_nop 0
	v_pk_add_f32 v[210:211], v[138:139], v[210:211]
	s_nop 0
	v_add_f32_e32 v210, v210, v211
	v_fmamk_f32 v210, v210, 0x3a000000, v1
	v_rsq_f32_e32 v166, v210
	s_waitcnt vmcnt(6)
	v_lshlrev_b32_e32 v139, 16, v182
	v_lshlrev_b32_e32 v138, 16, v180
	v_and_b32_e32 v141, 0xffff0000, v182
	v_and_b32_e32 v140, 0xffff0000, v180
	v_pk_add_f32 v[138:139], v[138:139], v[140:141]
	v_lshlrev_b32_e32 v141, 16, v183
	v_lshlrev_b32_e32 v140, 16, v181
	v_and_b32_e32 v183, 0xffff0000, v183
	v_and_b32_e32 v182, 0xffff0000, v181
	v_pk_add_f32 v[180:181], v[140:141], v[182:183]
	s_nop 0
	v_pk_add_f32 v[180:181], v[138:139], v[180:181]
	s_nop 0
	v_add_f32_e32 v180, v180, v181
	v_fmamk_f32 v180, v180, 0x3a000000, v1
	v_rsq_f32_e32 v162, v180
	s_waitcnt vmcnt(5)
	v_lshlrev_b32_e32 v139, 16, v186
	v_lshlrev_b32_e32 v138, 16, v184
	v_and_b32_e32 v141, 0xffff0000, v186
	v_and_b32_e32 v140, 0xffff0000, v184
	v_pk_add_f32 v[138:139], v[138:139], v[140:141]
	v_lshlrev_b32_e32 v141, 16, v187
	v_lshlrev_b32_e32 v140, 16, v185
	v_and_b32_e32 v187, 0xffff0000, v187
	v_and_b32_e32 v186, 0xffff0000, v185
	v_pk_add_f32 v[184:185], v[140:141], v[186:187]
	s_nop 0
	v_pk_add_f32 v[184:185], v[138:139], v[184:185]
	s_nop 0
	v_add_f32_e32 v184, v184, v185
	v_fmamk_f32 v184, v184, 0x3a000000, v1
	v_rsq_f32_e32 v158, v184
	s_waitcnt vmcnt(4)
	v_lshlrev_b32_e32 v139, 16, v190
	v_lshlrev_b32_e32 v138, 16, v188
	v_and_b32_e32 v141, 0xffff0000, v190
	v_and_b32_e32 v140, 0xffff0000, v188
	v_pk_add_f32 v[138:139], v[138:139], v[140:141]
	v_lshlrev_b32_e32 v141, 16, v191
	v_lshlrev_b32_e32 v140, 16, v189
	v_and_b32_e32 v191, 0xffff0000, v191
	v_and_b32_e32 v190, 0xffff0000, v189
	v_pk_add_f32 v[188:189], v[140:141], v[190:191]
	s_nop 0
	v_pk_add_f32 v[188:189], v[138:139], v[188:189]
	s_nop 0
	v_add_f32_e32 v188, v188, v189
	v_fmamk_f32 v188, v188, 0x3a000000, v1
	v_rsq_f32_e32 v154, v188
	s_waitcnt vmcnt(3)
	v_lshlrev_b32_e32 v139, 16, v194
	v_lshlrev_b32_e32 v138, 16, v192
	v_and_b32_e32 v141, 0xffff0000, v194
	v_and_b32_e32 v140, 0xffff0000, v192
	v_pk_add_f32 v[138:139], v[138:139], v[140:141]
	v_lshlrev_b32_e32 v141, 16, v195
	v_lshlrev_b32_e32 v140, 16, v193
	v_and_b32_e32 v195, 0xffff0000, v195
	v_and_b32_e32 v194, 0xffff0000, v193
	v_pk_add_f32 v[192:193], v[140:141], v[194:195]
	s_nop 0
	v_pk_add_f32 v[192:193], v[138:139], v[192:193]
	s_nop 0
	v_add_f32_e32 v192, v192, v193
	v_fmamk_f32 v192, v192, 0x3a000000, v1
	v_rsq_f32_e32 v150, v192
	s_waitcnt vmcnt(2)
	v_lshlrev_b32_e32 v139, 16, v198
	v_lshlrev_b32_e32 v138, 16, v196
	v_and_b32_e32 v141, 0xffff0000, v198
	v_and_b32_e32 v140, 0xffff0000, v196
	v_pk_add_f32 v[138:139], v[138:139], v[140:141]
	v_lshlrev_b32_e32 v141, 16, v199
	v_lshlrev_b32_e32 v140, 16, v197
	v_and_b32_e32 v199, 0xffff0000, v199
	v_and_b32_e32 v198, 0xffff0000, v197
	v_pk_add_f32 v[196:197], v[140:141], v[198:199]
	v_add_u32_e32 v140, 0xa0, v164
	v_pk_add_f32 v[196:197], v[138:139], v[196:197]
	v_ashrrev_i32_e32 v141, 31, v140
	v_add_f32_e32 v196, v196, v197
	v_fmamk_f32 v196, v196, 0x3a000000, v1
	v_rsq_f32_e32 v146, v196
	s_waitcnt vmcnt(1)
	v_lshlrev_b32_e32 v139, 16, v202
	v_lshlrev_b32_e32 v138, 16, v200
	v_and_b32_e32 v169, 0xffff0000, v202
	v_and_b32_e32 v168, 0xffff0000, v200
	v_pk_add_f32 v[138:139], v[138:139], v[168:169]
	v_lshlrev_b32_e32 v169, 16, v203
	v_lshlrev_b32_e32 v168, 16, v201
	v_and_b32_e32 v203, 0xffff0000, v203
	v_and_b32_e32 v202, 0xffff0000, v201
	v_pk_add_f32 v[200:201], v[168:169], v[202:203]
	s_nop 0
	v_pk_add_f32 v[200:201], v[138:139], v[200:201]
	v_add_u32_e32 v138, 0xb0, v164
	v_add_f32_e32 v200, v200, v201
	v_fmamk_f32 v200, v200, 0x3a000000, v1
	v_ashrrev_i32_e32 v139, 31, v138
	v_rsq_f32_e32 v142, v200
	s_waitcnt vmcnt(0)
; __device__ __forceinline__ u32x4 pack8(const f32x4& a, const f32x4& b) { u32x4 w; w.x = cvt_pk_bf16(a[0], a[1]); w.y = cvt_pk_bf16(a[2], a[3]); w.z = cvt_pk_bf16(b[0], b[1]); w.w = cvt_pk_bf16(b[2], b[3]); return w; }
; __device__ __forceinline__ float expneg(float g) { return ex2(fminf(-g * 1.4426950408889634f, 80.f)); }
;     __device__ __forceinline__ void operator()(const f32x4 (&acc)[2][2][4][2], const Unit& u, int wr, int wc, int fr, int fq) const {
;     ...
;         for (int ai = 0; ai < 2; ++ai)
; #pragma unroll
;             for (int m = 0; m < 4; ++m) { f32x4 v[2]; const float rs = rsv[ai][m];
; #pragma unroll
;                 for (int n = 0; n < 2; ++n)
; #pragma unroll
;                     for (int i = 0; i < 4; ++i) { const float g = acc[ai][0][m][n][i] * rs; v[n][i] = g * __builtin_amdgcn_rcpf(1.f + expneg(g)) * (acc[ai][1][m][n][i] * rs); }
;                 *(u32x4*)(act + (size_t)(rowt + ai * HALF + m * 16) * 5632 + col0) = pack8(v[0], v[1]); }
	v_lshlrev_b32_e32 v169, 16, v132
	v_lshlrev_b32_e32 v168, 16, v130
	v_and_b32_e32 v171, 0xffff0000, v132
	v_and_b32_e32 v170, 0xffff0000, v130
	v_pk_add_f32 v[168:169], v[168:169], v[170:171]
	v_lshlrev_b32_e32 v171, 16, v133
	v_lshlrev_b32_e32 v170, 16, v131
	v_and_b32_e32 v133, 0xffff0000, v133
	v_and_b32_e32 v132, 0xffff0000, v131
	v_pk_add_f32 v[130:131], v[170:171], v[132:133]
	s_nop 0
	v_pk_add_f32 v[130:131], v[168:169], v[130:131]
	v_mov_b32_e32 v168, v122
	v_mov_b32_e32 v169, v126
	v_pk_mul_f32 v[168:169], v[168:169], v[166:167] op_sel_hi:[1,0]
	v_add_f32_e32 v130, v130, v131
	v_mul_f32_e32 v122, 0xbfb8aa3b, v169
	v_min_f32_e32 v122, 0x42a00000, v122
	v_exp_f32_e32 v122, v122
	v_and_or_b32 v131, v151, 24, s2
	v_mov_b32_e32 v126, v123
	v_or_b32_e32 v132, s92, v131
	v_add_f32_e32 v122, 1.0, v122
	v_rcp_f32_e32 v122, v122
	v_ashrrev_i32_e32 v133, 31, v132
	v_fmamk_f32 v130, v130, 0x3a000000, v1
	v_rsq_f32_e32 v130, v130
	v_mul_f32_e32 v122, v169, v122
	v_mul_f32_e32 v131, v168, v122
	v_pk_mul_f32 v[122:123], v[126:127], v[166:167] op_sel_hi:[1,0]
	s_nop 0
	v_mul_f32_e32 v126, 0xbfb8aa3b, v123
	v_min_f32_e32 v126, 0x42a00000, v126
	v_exp_f32_e32 v126, v126
	s_nop 0
	v_add_f32_e32 v126, 1.0, v126
	v_rcp_f32_e32 v126, v126
	s_nop 0
	v_mul_f32_e32 v123, v123, v126
	v_mul_f32_e32 v126, v122, v123
	v_mov_b32_e32 v122, v124
	v_mov_b32_e32 v123, v128
	v_pk_mul_f32 v[122:123], v[122:123], v[166:167] op_sel_hi:[1,0]
	v_mov_b32_e32 v128, v125
	v_mul_f32_e32 v124, 0xbfb8aa3b, v123
	v_min_f32_e32 v124, 0x42a00000, v124
	v_exp_f32_e32 v124, v124
	s_nop 0
	v_add_f32_e32 v124, 1.0, v124
	v_rcp_f32_e32 v124, v124
	s_nop 0
	v_mul_f32_e32 v123, v123, v124
	v_mul_f32_e32 v124, v122, v123
	v_pk_mul_f32 v[122:123], v[128:129], v[166:167] op_sel_hi:[1,0]
	s_nop 0
	v_mul_f32_e32 v125, 0xbfb8aa3b, v123
	v_min_f32_e32 v125, 0x42a00000, v125
	v_exp_f32_e32 v125, v125
	s_nop 0
	v_add_f32_e32 v125, 1.0, v125
	v_rcp_f32_e32 v125, v125
	s_nop 0
	v_mul_f32_e32 v123, v123, v125
	v_mul_f32_e32 v125, v122, v123
	v_mov_b32_e32 v122, v114
	v_mov_b32_e32 v123, v118
	v_pk_mul_f32 v[122:123], v[122:123], v[166:167] op_sel_hi:[1,0]
	v_mov_b32_e32 v118, v115
	v_mul_f32_e32 v114, 0xbfb8aa3b, v123
	v_min_f32_e32 v114, 0x42a00000, v114
	v_exp_f32_e32 v114, v114
	s_nop 0
	v_add_f32_e32 v114, 1.0, v114
	v_rcp_f32_e32 v114, v114
	s_nop 0
	v_mul_f32_e32 v114, v123, v114
	v_mul_f32_e32 v122, v122, v114
	v_pk_mul_f32 v[114:115], v[118:119], v[166:167] op_sel_hi:[1,0]
	s_nop 0
	v_mul_f32_e32 v118, 0xbfb8aa3b, v115
	v_min_f32_e32 v118, 0x42a00000, v118
	v_exp_f32_e32 v118, v118
	s_nop 0
	v_add_f32_e32 v118, 1.0, v118
	v_rcp_f32_e32 v118, v118
	s_nop 0
	v_mul_f32_e32 v115, v115, v118
	v_mul_f32_e32 v123, v114, v115
	v_mov_b32_e32 v114, v116
	v_mov_b32_e32 v115, v120
	v_pk_mul_f32 v[114:115], v[114:115], v[166:167] op_sel_hi:[1,0]
	v_mov_b32_e32 v120, v117
	v_mul_f32_e32 v116, 0xbfb8aa3b, v115
	v_min_f32_e32 v116, 0x42a00000, v116
	v_exp_f32_e32 v116, v116
	v_cvt_pk_bf16_f32 v118, v131, v126
	v_cvt_pk_bf16_f32 v119, v124, v125
	s_nop 0
	v_add_f32_e32 v116, 1.0, v116
	v_rcp_f32_e32 v116, v116
	s_nop 0
	v_mul_f32_e32 v115, v115, v116
	v_mul_f32_e32 v116, v114, v115
	v_pk_mul_f32 v[114:115], v[120:121], v[166:167] op_sel_hi:[1,0]
	v_cvt_pk_bf16_f32 v120, v122, v123
	s_nop 0
	v_mul_f32_e32 v117, 0xbfb8aa3b, v115
	v_min_f32_e32 v117, 0x42a00000, v117
	v_exp_f32_e32 v117, v117
	s_nop 0
	v_add_f32_e32 v117, 1.0, v117
	v_rcp_f32_e32 v117, v117
	s_nop 0
	v_mul_f32_e32 v115, v115, v117
	v_mul_f32_e32 v114, v114, v115
	v_cvt_pk_bf16_f32 v121, v116, v114
	v_mov_b64_e32 v[114:115], s[18:19]
	v_mad_i64_i32 v[122:123], s[2:3], v164, s49, v[114:115]
	v_lshlrev_b64 v[116:117], 1, v[132:133]
	v_lshl_add_u64 v[122:123], v[122:123], 0, v[116:117]
	global_store_dwordx4 v[122:123], v[118:121], off
	s_nop 1
	v_mov_b32_e32 v118, v106
	v_mov_b32_e32 v119, v110
	v_pk_mul_f32 v[118:119], v[118:119], v[162:163] op_sel_hi:[1,0]
	v_mov_b32_e32 v110, v107
	v_mul_f32_e32 v106, 0xbfb8aa3b, v119
	v_min_f32_e32 v106, 0x42a00000, v106
	v_exp_f32_e32 v106, v106
	s_nop 0
	v_add_f32_e32 v106, 1.0, v106
	v_rcp_f32_e32 v106, v106
	s_nop 0
	v_mul_f32_e32 v106, v119, v106
	v_mul_f32_e32 v118, v118, v106
	v_pk_mul_f32 v[106:107], v[110:111], v[162:163] op_sel_hi:[1,0]
	s_nop 0
	v_mul_f32_e32 v110, 0xbfb8aa3b, v107
	v_min_f32_e32 v110, 0x42a00000, v110
	v_exp_f32_e32 v110, v110
	s_nop 0
	v_add_f32_e32 v110, 1.0, v110
	v_rcp_f32_e32 v110, v110
	s_nop 0
	v_mul_f32_e32 v107, v107, v110
	v_mul_f32_e32 v110, v106, v107
	v_mov_b32_e32 v106, v108
	v_mov_b32_e32 v107, v112
	v_pk_mul_f32 v[106:107], v[106:107], v[162:163] op_sel_hi:[1,0]
	v_mov_b32_e32 v112, v109
	v_mul_f32_e32 v108, 0xbfb8aa3b, v107
	v_min_f32_e32 v108, 0x42a00000, v108
	v_exp_f32_e32 v108, v108
	s_nop 0
	v_add_f32_e32 v108, 1.0, v108
	v_rcp_f32_e32 v108, v108
	s_nop 0
	v_mul_f32_e32 v107, v107, v108
	v_mul_f32_e32 v108, v106, v107
	v_pk_mul_f32 v[106:107], v[112:113], v[162:163] op_sel_hi:[1,0]
	s_nop 0
	v_mul_f32_e32 v109, 0xbfb8aa3b, v107
	v_min_f32_e32 v109, 0x42a00000, v109
	v_exp_f32_e32 v109, v109
	s_nop 0
	v_add_f32_e32 v109, 1.0, v109
	v_rcp_f32_e32 v109, v109
	s_nop 0
	v_mul_f32_e32 v107, v107, v109
	v_mul_f32_e32 v109, v106, v107
	v_mov_b32_e32 v106, v98
	v_mov_b32_e32 v107, v102
	v_pk_mul_f32 v[106:107], v[106:107], v[162:163] op_sel_hi:[1,0]
	v_mov_b32_e32 v102, v99
	v_mul_f32_e32 v98, 0xbfb8aa3b, v107
	v_min_f32_e32 v98, 0x42a00000, v98
	v_exp_f32_e32 v98, v98
	s_nop 0
	v_add_f32_e32 v98, 1.0, v98
	v_rcp_f32_e32 v98, v98
	s_nop 0
	v_mul_f32_e32 v98, v107, v98
	v_mul_f32_e32 v106, v106, v98
	v_pk_mul_f32 v[98:99], v[102:103], v[162:163] op_sel_hi:[1,0]
; __device__ __forceinline__ u32x4 pack8(const f32x4& a, const f32x4& b) { u32x4 w; w.x = cvt_pk_bf16(a[0], a[1]); w.y = cvt_pk_bf16(a[2], a[3]); w.z = cvt_pk_bf16(b[0], b[1]); w.w = cvt_pk_bf16(b[2], b[3]); return w; }
; __device__ __forceinline__ float expneg(float g) { return ex2(fminf(-g * 1.4426950408889634f, 80.f)); }
;     __device__ __forceinline__ void operator()(const f32x4 (&acc)[2][2][4][2], const Unit& u, int wr, int wc, int fr, int fq) const {
;     ...
;         for (int ai = 0; ai < 2; ++ai)
; #pragma unroll
;             for (int m = 0; m < 4; ++m) { f32x4 v[2]; const float rs = rsv[ai][m];
; #pragma unroll
;                 for (int n = 0; n < 2; ++n)
; #pragma unroll
;                     for (int i = 0; i < 4; ++i) { const float g = acc[ai][0][m][n][i] * rs; v[n][i] = g * __builtin_amdgcn_rcpf(1.f + expneg(g)) * (acc[ai][1][m][n][i] * rs); }
;                 *(u32x4*)(act + (size_t)(rowt + ai * HALF + m * 16) * 5632 + col0) = pack8(v[0], v[1]); }
	s_nop 0
	v_mul_f32_e32 v102, 0xbfb8aa3b, v99
	v_min_f32_e32 v102, 0x42a00000, v102
	v_exp_f32_e32 v102, v102
	s_nop 0
	v_add_f32_e32 v102, 1.0, v102
	v_rcp_f32_e32 v102, v102
	s_nop 0
	v_mul_f32_e32 v99, v99, v102
	v_mul_f32_e32 v102, v98, v99
	v_mov_b32_e32 v98, v100
	v_mov_b32_e32 v99, v104
	v_pk_mul_f32 v[98:99], v[98:99], v[162:163] op_sel_hi:[1,0]
	v_mov_b32_e32 v104, v101
	v_mul_f32_e32 v100, 0xbfb8aa3b, v99
	v_min_f32_e32 v100, 0x42a00000, v100
	v_exp_f32_e32 v100, v100
	s_nop 0
	v_add_f32_e32 v100, 1.0, v100
	v_rcp_f32_e32 v100, v100
	s_nop 0
	v_mul_f32_e32 v99, v99, v100
	v_mul_f32_e32 v103, v98, v99
	v_pk_mul_f32 v[98:99], v[104:105], v[162:163] op_sel_hi:[1,0]
	s_nop 0
	v_mul_f32_e32 v100, 0xbfb8aa3b, v99
	v_min_f32_e32 v100, 0x42a00000, v100
	v_exp_f32_e32 v100, v100
	s_nop 0
	v_add_f32_e32 v100, 1.0, v100
	v_rcp_f32_e32 v100, v100
	s_nop 0
	v_mul_f32_e32 v99, v99, v100
	v_mul_f32_e32 v101, v98, v99
	v_cvt_pk_bf16_f32 v98, v118, v110
	v_cvt_pk_bf16_f32 v99, v108, v109
	v_cvt_pk_bf16_f32 v100, v106, v102
	v_cvt_pk_bf16_f32 v101, v103, v101
	v_mad_i64_i32 v[102:103], s[2:3], v160, s49, v[114:115]
	v_lshl_add_u64 v[102:103], v[102:103], 0, v[116:117]
	global_store_dwordx4 v[102:103], v[98:101], off
	s_nop 1
	v_mov_b32_e32 v98, v90
	v_mov_b32_e32 v99, v94
	v_pk_mul_f32 v[98:99], v[98:99], v[158:159] op_sel_hi:[1,0]
	v_mov_b32_e32 v94, v91
	v_mul_f32_e32 v90, 0xbfb8aa3b, v99
	v_min_f32_e32 v90, 0x42a00000, v90
	v_exp_f32_e32 v90, v90
	s_nop 0
	v_add_f32_e32 v90, 1.0, v90
	v_rcp_f32_e32 v90, v90
	s_nop 0
	v_mul_f32_e32 v90, v99, v90
	v_mul_f32_e32 v98, v98, v90
	v_pk_mul_f32 v[90:91], v[94:95], v[158:159] op_sel_hi:[1,0]
	s_nop 0
	v_mul_f32_e32 v94, 0xbfb8aa3b, v91
	v_min_f32_e32 v94, 0x42a00000, v94
	v_exp_f32_e32 v94, v94
	s_nop 0
	v_add_f32_e32 v94, 1.0, v94
	v_rcp_f32_e32 v94, v94
	s_nop 0
	v_mul_f32_e32 v91, v91, v94
	v_mul_f32_e32 v94, v90, v91
	v_mov_b32_e32 v90, v92
	v_mov_b32_e32 v91, v96
	v_pk_mul_f32 v[90:91], v[90:91], v[158:159] op_sel_hi:[1,0]
	v_mov_b32_e32 v96, v93
	v_mul_f32_e32 v92, 0xbfb8aa3b, v91
	v_min_f32_e32 v92, 0x42a00000, v92
	v_exp_f32_e32 v92, v92
	s_nop 0
	v_add_f32_e32 v92, 1.0, v92
	v_rcp_f32_e32 v92, v92
	s_nop 0
	v_mul_f32_e32 v91, v91, v92
	v_mul_f32_e32 v92, v90, v91
	v_pk_mul_f32 v[90:91], v[96:97], v[158:159] op_sel_hi:[1,0]
	s_nop 0
	v_mul_f32_e32 v93, 0xbfb8aa3b, v91
	v_min_f32_e32 v93, 0x42a00000, v93
	v_exp_f32_e32 v93, v93
	s_nop 0
	v_add_f32_e32 v93, 1.0, v93
	v_rcp_f32_e32 v93, v93
	s_nop 0
	v_mul_f32_e32 v91, v91, v93
	v_mul_f32_e32 v93, v90, v91
	v_mov_b32_e32 v90, v82
	v_mov_b32_e32 v91, v86
	v_pk_mul_f32 v[90:91], v[90:91], v[158:159] op_sel_hi:[1,0]
	v_mov_b32_e32 v86, v83
	v_mul_f32_e32 v82, 0xbfb8aa3b, v91
	v_min_f32_e32 v82, 0x42a00000, v82
	v_exp_f32_e32 v82, v82
	s_nop 0
	v_add_f32_e32 v82, 1.0, v82
	v_rcp_f32_e32 v82, v82
	s_nop 0
	v_mul_f32_e32 v82, v91, v82
	v_mul_f32_e32 v90, v90, v82
	v_pk_mul_f32 v[82:83], v[86:87], v[158:159] op_sel_hi:[1,0]
	s_nop 0
	v_mul_f32_e32 v86, 0xbfb8aa3b, v83
	v_min_f32_e32 v86, 0x42a00000, v86
	v_exp_f32_e32 v86, v86
	s_nop 0
	v_add_f32_e32 v86, 1.0, v86
	v_rcp_f32_e32 v86, v86
	s_nop 0
	v_mul_f32_e32 v83, v83, v86
	v_mul_f32_e32 v86, v82, v83
	v_mov_b32_e32 v82, v84
	v_mov_b32_e32 v83, v88
	v_pk_mul_f32 v[82:83], v[82:83], v[158:159] op_sel_hi:[1,0]
	v_mov_b32_e32 v88, v85
	v_mul_f32_e32 v84, 0xbfb8aa3b, v83
	v_min_f32_e32 v84, 0x42a00000, v84
	v_exp_f32_e32 v84, v84
	s_nop 0
	v_add_f32_e32 v84, 1.0, v84
	v_rcp_f32_e32 v84, v84
	s_nop 0
	v_mul_f32_e32 v83, v83, v84
	v_mul_f32_e32 v87, v82, v83
	v_pk_mul_f32 v[82:83], v[88:89], v[158:159] op_sel_hi:[1,0]
	s_nop 0
	v_mul_f32_e32 v84, 0xbfb8aa3b, v83
	v_min_f32_e32 v84, 0x42a00000, v84
	v_exp_f32_e32 v84, v84
	s_nop 0
	v_add_f32_e32 v84, 1.0, v84
	v_rcp_f32_e32 v84, v84
	s_nop 0
	v_mul_f32_e32 v83, v83, v84
	v_mul_f32_e32 v85, v82, v83
	v_cvt_pk_bf16_f32 v82, v98, v94
	v_cvt_pk_bf16_f32 v83, v92, v93
	v_cvt_pk_bf16_f32 v84, v90, v86
	v_cvt_pk_bf16_f32 v85, v87, v85
	v_mad_i64_i32 v[86:87], s[2:3], v156, s49, v[114:115]
	v_lshl_add_u64 v[86:87], v[86:87], 0, v[116:117]
	global_store_dwordx4 v[86:87], v[82:85], off
	s_nop 1
	v_mov_b32_e32 v82, v74
	v_mov_b32_e32 v83, v78
	v_pk_mul_f32 v[82:83], v[82:83], v[154:155] op_sel_hi:[1,0]
	v_mov_b32_e32 v78, v75
	v_mul_f32_e32 v74, 0xbfb8aa3b, v83
	v_min_f32_e32 v74, 0x42a00000, v74
	v_exp_f32_e32 v74, v74
	s_nop 0
	v_add_f32_e32 v74, 1.0, v74
	v_rcp_f32_e32 v74, v74
	s_nop 0
	v_mul_f32_e32 v74, v83, v74
	v_mul_f32_e32 v82, v82, v74
	v_pk_mul_f32 v[74:75], v[78:79], v[154:155] op_sel_hi:[1,0]
	s_nop 0
	v_mul_f32_e32 v78, 0xbfb8aa3b, v75
	v_min_f32_e32 v78, 0x42a00000, v78
	v_exp_f32_e32 v78, v78
	s_nop 0
	v_add_f32_e32 v78, 1.0, v78
	v_rcp_f32_e32 v78, v78
	s_nop 0
	v_mul_f32_e32 v75, v75, v78
	v_mul_f32_e32 v78, v74, v75
	v_mov_b32_e32 v74, v76
	v_mov_b32_e32 v75, v80
	v_pk_mul_f32 v[74:75], v[74:75], v[154:155] op_sel_hi:[1,0]
	v_mov_b32_e32 v80, v77
	v_mul_f32_e32 v76, 0xbfb8aa3b, v75
	v_min_f32_e32 v76, 0x42a00000, v76
	v_exp_f32_e32 v76, v76
	s_nop 0
	v_add_f32_e32 v76, 1.0, v76
	v_rcp_f32_e32 v76, v76
	s_nop 0
	v_mul_f32_e32 v75, v75, v76
	v_mul_f32_e32 v76, v74, v75
	v_pk_mul_f32 v[74:75], v[80:81], v[154:155] op_sel_hi:[1,0]
	s_nop 0
	v_mul_f32_e32 v77, 0xbfb8aa3b, v75
	v_min_f32_e32 v77, 0x42a00000, v77
	v_exp_f32_e32 v77, v77
	s_nop 0
	v_add_f32_e32 v77, 1.0, v77
	v_rcp_f32_e32 v77, v77
	s_nop 0
	v_mul_f32_e32 v75, v75, v77
	v_mul_f32_e32 v77, v74, v75
	v_mov_b32_e32 v74, v66
	v_mov_b32_e32 v75, v70
	v_pk_mul_f32 v[74:75], v[74:75], v[154:155] op_sel_hi:[1,0]
	v_mov_b32_e32 v70, v67
	v_mul_f32_e32 v66, 0xbfb8aa3b, v75
	v_min_f32_e32 v66, 0x42a00000, v66
; __device__ __forceinline__ u32x4 pack8(const f32x4& a, const f32x4& b) { u32x4 w; w.x = cvt_pk_bf16(a[0], a[1]); w.y = cvt_pk_bf16(a[2], a[3]); w.z = cvt_pk_bf16(b[0], b[1]); w.w = cvt_pk_bf16(b[2], b[3]); return w; }
; __device__ __forceinline__ float expneg(float g) { return ex2(fminf(-g * 1.4426950408889634f, 80.f)); }
;     __device__ __forceinline__ void operator()(const f32x4 (&acc)[2][2][4][2], const Unit& u, int wr, int wc, int fr, int fq) const {
;     ...
;         for (int ai = 0; ai < 2; ++ai)
; #pragma unroll
;             for (int m = 0; m < 4; ++m) { f32x4 v[2]; const float rs = rsv[ai][m];
; #pragma unroll
;                 for (int n = 0; n < 2; ++n)
; #pragma unroll
;                     for (int i = 0; i < 4; ++i) { const float g = acc[ai][0][m][n][i] * rs; v[n][i] = g * __builtin_amdgcn_rcpf(1.f + expneg(g)) * (acc[ai][1][m][n][i] * rs); }
;                 *(u32x4*)(act + (size_t)(rowt + ai * HALF + m * 16) * 5632 + col0) = pack8(v[0], v[1]); }
	v_exp_f32_e32 v66, v66
	s_nop 0
	v_add_f32_e32 v66, 1.0, v66
	v_rcp_f32_e32 v66, v66
	s_nop 0
	v_mul_f32_e32 v66, v75, v66
	v_mul_f32_e32 v74, v74, v66
	v_pk_mul_f32 v[66:67], v[70:71], v[154:155] op_sel_hi:[1,0]
	s_nop 0
	v_mul_f32_e32 v70, 0xbfb8aa3b, v67
	v_min_f32_e32 v70, 0x42a00000, v70
	v_exp_f32_e32 v70, v70
	s_nop 0
	v_add_f32_e32 v70, 1.0, v70
	v_rcp_f32_e32 v70, v70
	s_nop 0
	v_mul_f32_e32 v67, v67, v70
	v_mul_f32_e32 v70, v66, v67
	v_mov_b32_e32 v66, v68
	v_mov_b32_e32 v67, v72
	v_pk_mul_f32 v[66:67], v[66:67], v[154:155] op_sel_hi:[1,0]
	v_mov_b32_e32 v72, v69
	v_mul_f32_e32 v68, 0xbfb8aa3b, v67
	v_min_f32_e32 v68, 0x42a00000, v68
	v_exp_f32_e32 v68, v68
	s_nop 0
	v_add_f32_e32 v68, 1.0, v68
	v_rcp_f32_e32 v68, v68
	s_nop 0
	v_mul_f32_e32 v67, v67, v68
	v_mul_f32_e32 v71, v66, v67
	v_pk_mul_f32 v[66:67], v[72:73], v[154:155] op_sel_hi:[1,0]
	s_nop 0
	v_mul_f32_e32 v68, 0xbfb8aa3b, v67
	v_min_f32_e32 v68, 0x42a00000, v68
	v_exp_f32_e32 v68, v68
	s_nop 0
	v_add_f32_e32 v68, 1.0, v68
	v_rcp_f32_e32 v68, v68
	s_nop 0
	v_mul_f32_e32 v67, v67, v68
	v_mul_f32_e32 v69, v66, v67
	v_cvt_pk_bf16_f32 v66, v82, v78
	v_cvt_pk_bf16_f32 v67, v76, v77
	v_cvt_pk_bf16_f32 v68, v74, v70
	v_cvt_pk_bf16_f32 v69, v71, v69
	v_mad_i64_i32 v[70:71], s[2:3], v152, s49, v[114:115]
	v_lshl_add_u64 v[70:71], v[70:71], 0, v[116:117]
	global_store_dwordx4 v[70:71], v[66:69], off
	s_nop 1
	v_mov_b32_e32 v66, v58
	v_mov_b32_e32 v67, v62
	v_pk_mul_f32 v[66:67], v[66:67], v[150:151] op_sel_hi:[1,0]
	v_mov_b32_e32 v62, v59
	v_mul_f32_e32 v58, 0xbfb8aa3b, v67
	v_min_f32_e32 v58, 0x42a00000, v58
	v_exp_f32_e32 v58, v58
	s_nop 0
	v_add_f32_e32 v58, 1.0, v58
	v_rcp_f32_e32 v58, v58
	s_nop 0
	v_mul_f32_e32 v58, v67, v58
	v_mul_f32_e32 v66, v66, v58
	v_pk_mul_f32 v[58:59], v[62:63], v[150:151] op_sel_hi:[1,0]
	s_nop 0
	v_mul_f32_e32 v62, 0xbfb8aa3b, v59
	v_min_f32_e32 v62, 0x42a00000, v62
	v_exp_f32_e32 v62, v62
	s_nop 0
	v_add_f32_e32 v62, 1.0, v62
	v_rcp_f32_e32 v62, v62
	s_nop 0
	v_mul_f32_e32 v59, v59, v62
	v_mul_f32_e32 v62, v58, v59
	v_mov_b32_e32 v58, v60
	v_mov_b32_e32 v59, v64
	v_pk_mul_f32 v[58:59], v[58:59], v[150:151] op_sel_hi:[1,0]
	v_mov_b32_e32 v64, v61
	v_mul_f32_e32 v60, 0xbfb8aa3b, v59
	v_min_f32_e32 v60, 0x42a00000, v60
	v_exp_f32_e32 v60, v60
	s_nop 0
	v_add_f32_e32 v60, 1.0, v60
	v_rcp_f32_e32 v60, v60
	s_nop 0
	v_mul_f32_e32 v59, v59, v60
	v_mul_f32_e32 v60, v58, v59
	v_pk_mul_f32 v[58:59], v[64:65], v[150:151] op_sel_hi:[1,0]
	s_nop 0
	v_mul_f32_e32 v61, 0xbfb8aa3b, v59
	v_min_f32_e32 v61, 0x42a00000, v61
	v_exp_f32_e32 v61, v61
	s_nop 0
	v_add_f32_e32 v61, 1.0, v61
	v_rcp_f32_e32 v61, v61
	s_nop 0
	v_mul_f32_e32 v59, v59, v61
	v_mul_f32_e32 v61, v58, v59
	v_mov_b32_e32 v58, v50
	v_mov_b32_e32 v59, v54
	v_pk_mul_f32 v[58:59], v[58:59], v[150:151] op_sel_hi:[1,0]
	v_mov_b32_e32 v54, v51
	v_mul_f32_e32 v50, 0xbfb8aa3b, v59
	v_min_f32_e32 v50, 0x42a00000, v50
	v_exp_f32_e32 v50, v50
	s_nop 0
	v_add_f32_e32 v50, 1.0, v50
	v_rcp_f32_e32 v50, v50
	s_nop 0
	v_mul_f32_e32 v50, v59, v50
	v_mul_f32_e32 v58, v58, v50
	v_pk_mul_f32 v[50:51], v[54:55], v[150:151] op_sel_hi:[1,0]
	s_nop 0
	v_mul_f32_e32 v54, 0xbfb8aa3b, v51
	v_min_f32_e32 v54, 0x42a00000, v54
	v_exp_f32_e32 v54, v54
	s_nop 0
	v_add_f32_e32 v54, 1.0, v54
	v_rcp_f32_e32 v54, v54
	s_nop 0
	v_mul_f32_e32 v51, v51, v54
	v_mul_f32_e32 v54, v50, v51
	v_mov_b32_e32 v50, v52
	v_mov_b32_e32 v51, v56
	v_pk_mul_f32 v[50:51], v[50:51], v[150:151] op_sel_hi:[1,0]
	v_mov_b32_e32 v56, v53
	v_mul_f32_e32 v52, 0xbfb8aa3b, v51
	v_min_f32_e32 v52, 0x42a00000, v52
	v_exp_f32_e32 v52, v52
	s_nop 0
	v_add_f32_e32 v52, 1.0, v52
	v_rcp_f32_e32 v52, v52
	s_nop 0
	v_mul_f32_e32 v51, v51, v52
	v_mul_f32_e32 v55, v50, v51
	v_pk_mul_f32 v[50:51], v[56:57], v[150:151] op_sel_hi:[1,0]
	s_nop 0
	v_mul_f32_e32 v52, 0xbfb8aa3b, v51
	v_min_f32_e32 v52, 0x42a00000, v52
	v_exp_f32_e32 v52, v52
	s_nop 0
	v_add_f32_e32 v52, 1.0, v52
	v_rcp_f32_e32 v52, v52
	s_nop 0
	v_mul_f32_e32 v51, v51, v52
	v_mul_f32_e32 v53, v50, v51
	v_cvt_pk_bf16_f32 v50, v66, v62
	v_cvt_pk_bf16_f32 v51, v60, v61
	v_cvt_pk_bf16_f32 v52, v58, v54
	v_cvt_pk_bf16_f32 v53, v55, v53
	v_mad_i64_i32 v[54:55], s[2:3], v148, s49, v[114:115]
	v_lshl_add_u64 v[54:55], v[54:55], 0, v[116:117]
	global_store_dwordx4 v[54:55], v[50:53], off
	s_nop 1
	v_mov_b32_e32 v50, v42
	v_mov_b32_e32 v51, v46
	v_pk_mul_f32 v[50:51], v[50:51], v[146:147] op_sel_hi:[1,0]
	v_mov_b32_e32 v46, v43
	v_mul_f32_e32 v42, 0xbfb8aa3b, v51
	v_min_f32_e32 v42, 0x42a00000, v42
	v_exp_f32_e32 v42, v42
	s_nop 0
	v_add_f32_e32 v42, 1.0, v42
	v_rcp_f32_e32 v42, v42
	s_nop 0
	v_mul_f32_e32 v42, v51, v42
	v_mul_f32_e32 v50, v50, v42
	v_pk_mul_f32 v[42:43], v[46:47], v[146:147] op_sel_hi:[1,0]
	s_nop 0
	v_mul_f32_e32 v46, 0xbfb8aa3b, v43
	v_min_f32_e32 v46, 0x42a00000, v46
	v_exp_f32_e32 v46, v46
	s_nop 0
	v_add_f32_e32 v46, 1.0, v46
	v_rcp_f32_e32 v46, v46
	s_nop 0
	v_mul_f32_e32 v43, v43, v46
	v_mul_f32_e32 v46, v42, v43
	v_mov_b32_e32 v42, v44
	v_mov_b32_e32 v43, v48
	v_pk_mul_f32 v[42:43], v[42:43], v[146:147] op_sel_hi:[1,0]
	v_mov_b32_e32 v48, v45
	v_mul_f32_e32 v44, 0xbfb8aa3b, v43
	v_min_f32_e32 v44, 0x42a00000, v44
	v_exp_f32_e32 v44, v44
	s_nop 0
	v_add_f32_e32 v44, 1.0, v44
	v_rcp_f32_e32 v44, v44
	s_nop 0
	v_mul_f32_e32 v43, v43, v44
	v_mul_f32_e32 v44, v42, v43
	v_pk_mul_f32 v[42:43], v[48:49], v[146:147] op_sel_hi:[1,0]
	s_nop 0
	v_mul_f32_e32 v45, 0xbfb8aa3b, v43
	v_min_f32_e32 v45, 0x42a00000, v45
	v_exp_f32_e32 v45, v45
	s_nop 0
	v_add_f32_e32 v45, 1.0, v45
	v_rcp_f32_e32 v45, v45
	s_nop 0
	v_mul_f32_e32 v43, v43, v45
	v_mul_f32_e32 v45, v42, v43
	v_mov_b32_e32 v42, v34
	v_mov_b32_e32 v43, v38
; __device__ __forceinline__ u32x4 pack8(const f32x4& a, const f32x4& b) { u32x4 w; w.x = cvt_pk_bf16(a[0], a[1]); w.y = cvt_pk_bf16(a[2], a[3]); w.z = cvt_pk_bf16(b[0], b[1]); w.w = cvt_pk_bf16(b[2], b[3]); return w; }
; __device__ __forceinline__ float expneg(float g) { return ex2(fminf(-g * 1.4426950408889634f, 80.f)); }
;     __device__ __forceinline__ void operator()(const f32x4 (&acc)[2][2][4][2], const Unit& u, int wr, int wc, int fr, int fq) const {
;     ...
;         for (int ai = 0; ai < 2; ++ai)
; #pragma unroll
;             for (int m = 0; m < 4; ++m) { f32x4 v[2]; const float rs = rsv[ai][m];
; #pragma unroll
;                 for (int n = 0; n < 2; ++n)
; #pragma unroll
;                     for (int i = 0; i < 4; ++i) { const float g = acc[ai][0][m][n][i] * rs; v[n][i] = g * __builtin_amdgcn_rcpf(1.f + expneg(g)) * (acc[ai][1][m][n][i] * rs); }
;                 *(u32x4*)(act + (size_t)(rowt + ai * HALF + m * 16) * 5632 + col0) = pack8(v[0], v[1]); }
	v_pk_mul_f32 v[42:43], v[42:43], v[146:147] op_sel_hi:[1,0]
	v_mov_b32_e32 v38, v35
	v_mul_f32_e32 v34, 0xbfb8aa3b, v43
	v_min_f32_e32 v34, 0x42a00000, v34
	v_exp_f32_e32 v34, v34
	s_nop 0
	v_add_f32_e32 v34, 1.0, v34
	v_rcp_f32_e32 v34, v34
	s_nop 0
	v_mul_f32_e32 v34, v43, v34
	v_mul_f32_e32 v42, v42, v34
	v_pk_mul_f32 v[34:35], v[38:39], v[146:147] op_sel_hi:[1,0]
	s_nop 0
	v_mul_f32_e32 v38, 0xbfb8aa3b, v35
	v_min_f32_e32 v38, 0x42a00000, v38
	v_exp_f32_e32 v38, v38
	s_nop 0
	v_add_f32_e32 v38, 1.0, v38
	v_rcp_f32_e32 v38, v38
	s_nop 0
	v_mul_f32_e32 v35, v35, v38
	v_mul_f32_e32 v38, v34, v35
	v_mov_b32_e32 v34, v36
	v_mov_b32_e32 v35, v40
	v_pk_mul_f32 v[34:35], v[34:35], v[146:147] op_sel_hi:[1,0]
	v_mov_b32_e32 v40, v37
	v_mul_f32_e32 v36, 0xbfb8aa3b, v35
	v_min_f32_e32 v36, 0x42a00000, v36
	v_exp_f32_e32 v36, v36
	s_nop 0
	v_add_f32_e32 v36, 1.0, v36
	v_rcp_f32_e32 v36, v36
	s_nop 0
	v_mul_f32_e32 v35, v35, v36
	v_mul_f32_e32 v39, v34, v35
	v_pk_mul_f32 v[34:35], v[40:41], v[146:147] op_sel_hi:[1,0]
	s_nop 0
	v_mul_f32_e32 v36, 0xbfb8aa3b, v35
	v_min_f32_e32 v36, 0x42a00000, v36
	v_exp_f32_e32 v36, v36
	s_nop 0
	v_add_f32_e32 v36, 1.0, v36
	v_rcp_f32_e32 v36, v36
	s_nop 0
	v_mul_f32_e32 v35, v35, v36
	v_mul_f32_e32 v37, v34, v35
	v_cvt_pk_bf16_f32 v34, v50, v46
	v_cvt_pk_bf16_f32 v35, v44, v45
	v_cvt_pk_bf16_f32 v36, v42, v38
	v_cvt_pk_bf16_f32 v37, v39, v37
	v_mad_i64_i32 v[38:39], s[2:3], v144, s49, v[114:115]
	v_lshl_add_u64 v[38:39], v[38:39], 0, v[116:117]
	global_store_dwordx4 v[38:39], v[34:37], off
	s_nop 1
	v_mov_b32_e32 v34, v26
	v_mov_b32_e32 v35, v30
	v_pk_mul_f32 v[34:35], v[34:35], v[142:143] op_sel_hi:[1,0]
	v_mov_b32_e32 v30, v27
	v_mul_f32_e32 v26, 0xbfb8aa3b, v35
	v_min_f32_e32 v26, 0x42a00000, v26
	v_exp_f32_e32 v26, v26
	s_nop 0
	v_add_f32_e32 v26, 1.0, v26
	v_rcp_f32_e32 v26, v26
	s_nop 0
	v_mul_f32_e32 v26, v35, v26
	v_mul_f32_e32 v34, v34, v26
	v_pk_mul_f32 v[26:27], v[30:31], v[142:143] op_sel_hi:[1,0]
	s_nop 0
	v_mul_f32_e32 v30, 0xbfb8aa3b, v27
	v_min_f32_e32 v30, 0x42a00000, v30
	v_exp_f32_e32 v30, v30
	s_nop 0
	v_add_f32_e32 v30, 1.0, v30
	v_rcp_f32_e32 v30, v30
	s_nop 0
	v_mul_f32_e32 v27, v27, v30
	v_mul_f32_e32 v30, v26, v27
	v_mov_b32_e32 v26, v28
	v_mov_b32_e32 v27, v32
	v_pk_mul_f32 v[26:27], v[26:27], v[142:143] op_sel_hi:[1,0]
	v_mov_b32_e32 v32, v29
	v_mul_f32_e32 v28, 0xbfb8aa3b, v27
	v_min_f32_e32 v28, 0x42a00000, v28
	v_exp_f32_e32 v28, v28
	s_nop 0
	v_add_f32_e32 v28, 1.0, v28
	v_rcp_f32_e32 v28, v28
	s_nop 0
	v_mul_f32_e32 v27, v27, v28
	v_mul_f32_e32 v28, v26, v27
	v_pk_mul_f32 v[26:27], v[32:33], v[142:143] op_sel_hi:[1,0]
	s_nop 0
	v_mul_f32_e32 v29, 0xbfb8aa3b, v27
	v_min_f32_e32 v29, 0x42a00000, v29
	v_exp_f32_e32 v29, v29
	s_nop 0
	v_add_f32_e32 v29, 1.0, v29
	v_rcp_f32_e32 v29, v29
	s_nop 0
	v_mul_f32_e32 v27, v27, v29
	v_mul_f32_e32 v29, v26, v27
	v_mov_b32_e32 v26, v18
	v_mov_b32_e32 v27, v22
	v_pk_mul_f32 v[26:27], v[26:27], v[142:143] op_sel_hi:[1,0]
	v_mov_b32_e32 v22, v19
	v_mul_f32_e32 v18, 0xbfb8aa3b, v27
	v_min_f32_e32 v18, 0x42a00000, v18
	v_exp_f32_e32 v18, v18
	s_nop 0
	v_add_f32_e32 v18, 1.0, v18
	v_rcp_f32_e32 v18, v18
	s_nop 0
	v_mul_f32_e32 v18, v27, v18
	v_mul_f32_e32 v26, v26, v18
	v_pk_mul_f32 v[18:19], v[22:23], v[142:143] op_sel_hi:[1,0]
	s_nop 0
	v_mul_f32_e32 v22, 0xbfb8aa3b, v19
	v_min_f32_e32 v22, 0x42a00000, v22
	v_exp_f32_e32 v22, v22
	s_nop 0
	v_add_f32_e32 v22, 1.0, v22
	v_rcp_f32_e32 v22, v22
	s_nop 0
	v_mul_f32_e32 v19, v19, v22
	v_mul_f32_e32 v22, v18, v19
	v_mov_b32_e32 v18, v20
	v_mov_b32_e32 v19, v24
	v_pk_mul_f32 v[18:19], v[18:19], v[142:143] op_sel_hi:[1,0]
	v_mov_b32_e32 v24, v21
	v_mul_f32_e32 v20, 0xbfb8aa3b, v19
; __device__ __forceinline__ u32x4 pack8(const f32x4& a, const f32x4& b) { u32x4 w; w.x = cvt_pk_bf16(a[0], a[1]); w.y = cvt_pk_bf16(a[2], a[3]); w.z = cvt_pk_bf16(b[0], b[1]); w.w = cvt_pk_bf16(b[2], b[3]); return w; }
; __device__ __forceinline__ float expneg(float g) { return ex2(fminf(-g * 1.4426950408889634f, 80.f)); }
;     __device__ __forceinline__ void operator()(const f32x4 (&acc)[2][2][4][2], const Unit& u, int wr, int wc, int fr, int fq) const {
;     ...
;         for (int ai = 0; ai < 2; ++ai)
; #pragma unroll
;             for (int m = 0; m < 4; ++m) { f32x4 v[2]; const float rs = rsv[ai][m];
; #pragma unroll
;                 for (int n = 0; n < 2; ++n)
; #pragma unroll
;                     for (int i = 0; i < 4; ++i) { const float g = acc[ai][0][m][n][i] * rs; v[n][i] = g * __builtin_amdgcn_rcpf(1.f + expneg(g)) * (acc[ai][1][m][n][i] * rs); }
;                 *(u32x4*)(act + (size_t)(rowt + ai * HALF + m * 16) * 5632 + col0) = pack8(v[0], v[1]); }
	v_min_f32_e32 v20, 0x42a00000, v20
	v_exp_f32_e32 v20, v20
	s_nop 0
	v_add_f32_e32 v20, 1.0, v20
	v_rcp_f32_e32 v20, v20
	s_nop 0
	v_mul_f32_e32 v19, v19, v20
	v_mul_f32_e32 v23, v18, v19
	v_pk_mul_f32 v[18:19], v[24:25], v[142:143] op_sel_hi:[1,0]
	s_nop 0
	v_mul_f32_e32 v20, 0xbfb8aa3b, v19
	v_min_f32_e32 v20, 0x42a00000, v20
	v_exp_f32_e32 v20, v20
	s_nop 0
	v_add_f32_e32 v20, 1.0, v20
	v_rcp_f32_e32 v20, v20
	s_nop 0
	v_mul_f32_e32 v19, v19, v20
	v_mul_f32_e32 v21, v18, v19
	v_cvt_pk_bf16_f32 v18, v34, v30
	v_cvt_pk_bf16_f32 v19, v28, v29
	v_cvt_pk_bf16_f32 v20, v26, v22
	v_cvt_pk_bf16_f32 v21, v23, v21
	v_mad_i64_i32 v[22:23], s[2:3], v140, s49, v[114:115]
	v_lshl_add_u64 v[22:23], v[22:23], 0, v[116:117]
	global_store_dwordx4 v[22:23], v[18:21], off
	s_nop 1
	v_mov_b32_e32 v18, v10
	v_mov_b32_e32 v19, v14
	v_pk_mul_f32 v[18:19], v[18:19], v[130:131] op_sel_hi:[1,0]
	v_mov_b32_e32 v14, v11
	v_mul_f32_e32 v10, 0xbfb8aa3b, v19
	v_min_f32_e32 v10, 0x42a00000, v10
	v_exp_f32_e32 v10, v10
	s_nop 0
	v_add_f32_e32 v10, 1.0, v10
	v_rcp_f32_e32 v10, v10
	s_nop 0
	v_mul_f32_e32 v10, v19, v10
	v_mul_f32_e32 v18, v18, v10
	v_pk_mul_f32 v[10:11], v[14:15], v[130:131] op_sel_hi:[1,0]
	s_nop 0
	v_mul_f32_e32 v14, 0xbfb8aa3b, v11
	v_min_f32_e32 v14, 0x42a00000, v14
	v_exp_f32_e32 v14, v14
	s_nop 0
	v_add_f32_e32 v14, 1.0, v14
	v_rcp_f32_e32 v14, v14
	s_nop 0
	v_mul_f32_e32 v11, v11, v14
	v_mul_f32_e32 v14, v10, v11
	v_mov_b32_e32 v10, v12
	v_mov_b32_e32 v11, v16
	v_pk_mul_f32 v[10:11], v[10:11], v[130:131] op_sel_hi:[1,0]
	v_mov_b32_e32 v16, v13
	v_mul_f32_e32 v12, 0xbfb8aa3b, v11
	v_min_f32_e32 v12, 0x42a00000, v12
	v_exp_f32_e32 v12, v12
	s_nop 0
	v_add_f32_e32 v12, 1.0, v12
	v_rcp_f32_e32 v12, v12
	s_nop 0
	v_mul_f32_e32 v11, v11, v12
	v_mul_f32_e32 v12, v10, v11
	v_pk_mul_f32 v[10:11], v[16:17], v[130:131] op_sel_hi:[1,0]
	s_nop 0
	v_mul_f32_e32 v13, 0xbfb8aa3b, v11
	v_min_f32_e32 v13, 0x42a00000, v13
	v_exp_f32_e32 v13, v13
	s_nop 0
	v_add_f32_e32 v13, 1.0, v13
	v_rcp_f32_e32 v13, v13
	s_nop 0
	v_mul_f32_e32 v11, v11, v13
	v_mul_f32_e32 v13, v10, v11
	v_mov_b32_e32 v10, v2
	v_mov_b32_e32 v11, v6
	v_pk_mul_f32 v[10:11], v[10:11], v[130:131] op_sel_hi:[1,0]
	v_mov_b32_e32 v6, v3
	v_mul_f32_e32 v2, 0xbfb8aa3b, v11
	v_min_f32_e32 v2, 0x42a00000, v2
	v_exp_f32_e32 v2, v2
	s_nop 0
	v_add_f32_e32 v2, 1.0, v2
	v_rcp_f32_e32 v2, v2
	s_nop 0
	v_mul_f32_e32 v2, v11, v2
	v_mul_f32_e32 v10, v10, v2
	v_pk_mul_f32 v[2:3], v[6:7], v[130:131] op_sel_hi:[1,0]
	s_nop 0
	v_mul_f32_e32 v6, 0xbfb8aa3b, v3
	v_min_f32_e32 v6, 0x42a00000, v6
	v_exp_f32_e32 v6, v6
	s_nop 0
	v_add_f32_e32 v6, 1.0, v6
	v_rcp_f32_e32 v6, v6
	s_nop 0
	v_mul_f32_e32 v3, v3, v6
	v_mul_f32_e32 v6, v2, v3
	v_mov_b32_e32 v2, v4
	v_mov_b32_e32 v3, v8
	v_pk_mul_f32 v[2:3], v[2:3], v[130:131] op_sel_hi:[1,0]
	v_mov_b32_e32 v8, v5
	v_mul_f32_e32 v4, 0xbfb8aa3b, v3
	v_min_f32_e32 v4, 0x42a00000, v4
	v_exp_f32_e32 v4, v4
	s_nop 0
	v_add_f32_e32 v4, 1.0, v4
	v_rcp_f32_e32 v4, v4
	s_nop 0
	v_mul_f32_e32 v3, v3, v4
	v_mul_f32_e32 v7, v2, v3
	v_pk_mul_f32 v[2:3], v[8:9], v[130:131] op_sel_hi:[1,0]
	s_nop 0
	v_mul_f32_e32 v4, 0xbfb8aa3b, v3
	v_min_f32_e32 v4, 0x42a00000, v4
	v_exp_f32_e32 v4, v4
	s_nop 0
	v_add_f32_e32 v4, 1.0, v4
	v_rcp_f32_e32 v4, v4
	s_nop 0
	v_mul_f32_e32 v3, v3, v4
	v_mul_f32_e32 v5, v2, v3
	v_cvt_pk_bf16_f32 v2, v18, v14
	v_cvt_pk_bf16_f32 v3, v12, v13
	v_cvt_pk_bf16_f32 v4, v10, v6
	v_cvt_pk_bf16_f32 v5, v7, v5
	v_mad_i64_i32 v[6:7], s[2:3], v138, s49, v[114:115]
	v_lshl_add_u64 v[6:7], v[6:7], 0, v[116:117]
	global_store_dwordx4 v[6:7], v[2:5], off
	s_cbranch_vccnz .LBB0_701
	s_andn2_b64 vcc, exec, s[16:17]
	s_cbranch_vccnz .LBB0_700
	s_barrier
	s_branch .LBB0_700
